# EpiRes GEMM epilogues (out/mlp2 residual) de-serialised: residual tiles loaded 6 units ahead into dead fragment VGPRs, gates loaded once, counted vmcnt
# baseline (speedup 1.0000x reference)
.LBB0_108:
	s_ashr_i32 s11, s39, 3
	s_mul_hi_i32 s13, s11, 0x6000
	s_mulk_i32 s11, 0x6000
	s_add_u32 s18, s31, s11
	s_addc_u32 s19, s34, s13
	v_readlane_b32 s20, v252, 25
	v_readlane_b32 s21, v252, 26
	v_lshl_add_u32 v154, s39, 8, v156
	v_lshl_add_u32 v155, s38, 8, v158
	v_lshlrev_b32_e32 v154, 12, v154
	v_lshlrev_b32_e32 v155, 2, v155
	v_add_u32_e32 v154, v154, v155
	s_andn2_b64 vcc, exec, s[6:7]
	s_waitcnt lgkmcnt(0)
	global_load_dwordx4 v[128:131], v155, s[18:19]
	global_load_dwordx4 v[132:135], v155, s[18:19] offset:16
	global_load_dwordx4 v[146:149], v155, s[18:19] offset:512
	global_load_dwordx4 v[150:153], v155, s[18:19] offset:528
	s_add_u32 s100, s20, 0x0
	s_addc_u32 s101, s21, 0
	global_load_dwordx4 v[166:169], v154, s[100:101]
	global_load_dwordx4 v[170:173], v154, s[100:101] offset:16
	s_add_u32 s100, s20, 0x10000
	s_addc_u32 s101, s21, 0
	global_load_dwordx4 v[174:177], v154, s[100:101]
	global_load_dwordx4 v[178:181], v154, s[100:101] offset:16
	s_add_u32 s100, s20, 0x20000
	s_addc_u32 s101, s21, 0
	global_load_dwordx4 v[182:185], v154, s[100:101]
	global_load_dwordx4 v[186:189], v154, s[100:101] offset:16
	s_add_u32 s100, s20, 0x30000
	s_addc_u32 s101, s21, 0
	global_load_dwordx4 v[190:193], v154, s[100:101]
	global_load_dwordx4 v[194:197], v154, s[100:101] offset:16
	s_add_u32 s100, s20, 0x80000
	s_addc_u32 s101, s21, 0
	global_load_dwordx4 v[198:201], v154, s[100:101]
	global_load_dwordx4 v[202:205], v154, s[100:101] offset:16
	s_add_u32 s100, s20, 0x90000
	s_addc_u32 s101, s21, 0
	global_load_dwordx4 v[228:231], v154, s[100:101]
	global_load_dwordx4 v[232:235], v154, s[100:101] offset:16
	s_waitcnt vmcnt(10)
	v_pk_fma_f32 v[166:167], v[124:125], v[128:129], v[166:167]
	v_pk_fma_f32 v[168:169], v[126:127], v[130:131], v[168:169]
	v_pk_fma_f32 v[170:171], v[120:121], v[132:133], v[170:171]
	v_pk_fma_f32 v[172:173], v[122:123], v[134:135], v[172:173]
	s_add_u32 s18, s8, 0x0
	s_addc_u32 s19, s9, 0
	global_store_dwordx4 v154, v[166:169], s[18:19]
	global_store_dwordx4 v154, v[170:173], s[18:19] offset:16
	s_add_u32 s100, s20, 0xa0000
	s_addc_u32 s101, s21, 0
	global_load_dwordx4 v[166:169], v154, s[100:101]
	global_load_dwordx4 v[170:173], v154, s[100:101] offset:16
	s_waitcnt vmcnt(12)
	v_pk_fma_f32 v[174:175], v[116:117], v[128:129], v[174:175]
	v_pk_fma_f32 v[176:177], v[118:119], v[130:131], v[176:177]
	v_pk_fma_f32 v[178:179], v[112:113], v[132:133], v[178:179]
	v_pk_fma_f32 v[180:181], v[114:115], v[134:135], v[180:181]
	s_add_u32 s18, s8, 0x10000
	s_addc_u32 s19, s9, 0
	global_store_dwordx4 v154, v[174:177], s[18:19]
	global_store_dwordx4 v154, v[178:181], s[18:19] offset:16
	s_add_u32 s100, s20, 0xb0000
	s_addc_u32 s101, s21, 0
	global_load_dwordx4 v[174:177], v154, s[100:101]
	global_load_dwordx4 v[178:181], v154, s[100:101] offset:16
	s_waitcnt vmcnt(14)
	v_pk_fma_f32 v[182:183], v[108:109], v[128:129], v[182:183]
	v_pk_fma_f32 v[184:185], v[110:111], v[130:131], v[184:185]
	v_pk_fma_f32 v[186:187], v[104:105], v[132:133], v[186:187]
	v_pk_fma_f32 v[188:189], v[106:107], v[134:135], v[188:189]
	s_add_u32 s18, s8, 0x20000
	s_addc_u32 s19, s9, 0
	global_store_dwordx4 v154, v[182:185], s[18:19]
	global_store_dwordx4 v154, v[186:189], s[18:19] offset:16
	s_add_u32 s100, s20, 0x0
	s_addc_u32 s101, s21, 0
	global_load_dwordx4 v[182:185], v154, s[100:101] offset:512
	global_load_dwordx4 v[186:189], v154, s[100:101] offset:528
	s_waitcnt vmcnt(16)
	v_pk_fma_f32 v[190:191], v[100:101], v[128:129], v[190:191]
	v_pk_fma_f32 v[192:193], v[102:103], v[130:131], v[192:193]
	v_pk_fma_f32 v[194:195], v[96:97], v[132:133], v[194:195]
	v_pk_fma_f32 v[196:197], v[98:99], v[134:135], v[196:197]
	s_add_u32 s18, s8, 0x30000
	s_addc_u32 s19, s9, 0
	global_store_dwordx4 v154, v[190:193], s[18:19]
	global_store_dwordx4 v154, v[194:197], s[18:19] offset:16
	s_add_u32 s100, s20, 0x10000
	s_addc_u32 s101, s21, 0
	global_load_dwordx4 v[190:193], v154, s[100:101] offset:512
	global_load_dwordx4 v[194:197], v154, s[100:101] offset:528
	s_waitcnt vmcnt(18)
	v_pk_fma_f32 v[198:199], v[92:93], v[128:129], v[198:199]
	v_pk_fma_f32 v[200:201], v[94:95], v[130:131], v[200:201]
	v_pk_fma_f32 v[202:203], v[88:89], v[132:133], v[202:203]
	v_pk_fma_f32 v[204:205], v[90:91], v[134:135], v[204:205]
	s_add_u32 s18, s8, 0x80000
	s_addc_u32 s19, s9, 0
	global_store_dwordx4 v154, v[198:201], s[18:19]
	global_store_dwordx4 v154, v[202:205], s[18:19] offset:16
	s_add_u32 s100, s20, 0x20000
	s_addc_u32 s101, s21, 0
	global_load_dwordx4 v[198:201], v154, s[100:101] offset:512
	global_load_dwordx4 v[202:205], v154, s[100:101] offset:528
	s_waitcnt vmcnt(20)
	v_pk_fma_f32 v[228:229], v[84:85], v[128:129], v[228:229]
	v_pk_fma_f32 v[230:231], v[86:87], v[130:131], v[230:231]
	v_pk_fma_f32 v[232:233], v[80:81], v[132:133], v[232:233]
	v_pk_fma_f32 v[234:235], v[82:83], v[134:135], v[234:235]
	s_add_u32 s18, s8, 0x90000
	s_addc_u32 s19, s9, 0
	global_store_dwordx4 v154, v[228:231], s[18:19]
	global_store_dwordx4 v154, v[232:235], s[18:19] offset:16
	s_add_u32 s100, s20, 0x30000
	s_addc_u32 s101, s21, 0
	global_load_dwordx4 v[228:231], v154, s[100:101] offset:512
	global_load_dwordx4 v[232:235], v154, s[100:101] offset:528
	s_waitcnt vmcnt(20)
	v_pk_fma_f32 v[166:167], v[76:77], v[128:129], v[166:167]
	v_pk_fma_f32 v[168:169], v[78:79], v[130:131], v[168:169]
	v_pk_fma_f32 v[170:171], v[72:73], v[132:133], v[170:171]
	v_pk_fma_f32 v[172:173], v[74:75], v[134:135], v[172:173]
	s_add_u32 s18, s8, 0xa0000
	s_addc_u32 s19, s9, 0
	global_store_dwordx4 v154, v[166:169], s[18:19]
	global_store_dwordx4 v154, v[170:173], s[18:19] offset:16
	s_add_u32 s100, s20, 0x80000
	s_addc_u32 s101, s21, 0
	global_load_dwordx4 v[166:169], v154, s[100:101] offset:512
	global_load_dwordx4 v[170:173], v154, s[100:101] offset:528
	s_waitcnt vmcnt(20)
	v_pk_fma_f32 v[174:175], v[68:69], v[128:129], v[174:175]
	v_pk_fma_f32 v[176:177], v[70:71], v[130:131], v[176:177]
	v_pk_fma_f32 v[178:179], v[56:57], v[132:133], v[178:179]
	v_pk_fma_f32 v[180:181], v[58:59], v[134:135], v[180:181]
	s_add_u32 s18, s8, 0xb0000
	s_addc_u32 s19, s9, 0
	global_store_dwordx4 v154, v[174:177], s[18:19]
	global_store_dwordx4 v154, v[178:181], s[18:19] offset:16
	s_add_u32 s100, s20, 0x90000
	s_addc_u32 s101, s21, 0
	global_load_dwordx4 v[174:177], v154, s[100:101] offset:512
	global_load_dwordx4 v[178:181], v154, s[100:101] offset:528
	s_waitcnt vmcnt(20)
	v_pk_fma_f32 v[182:183], v[64:65], v[146:147], v[182:183]
	v_pk_fma_f32 v[184:185], v[66:67], v[148:149], v[184:185]
	v_pk_fma_f32 v[186:187], v[60:61], v[150:151], v[186:187]
	v_pk_fma_f32 v[188:189], v[62:63], v[152:153], v[188:189]
	s_add_u32 s18, s8, 0x0
	s_addc_u32 s19, s9, 0
	global_store_dwordx4 v154, v[182:185], s[18:19] offset:512
	global_store_dwordx4 v154, v[186:189], s[18:19] offset:528
	s_add_u32 s100, s20, 0xa0000
	s_addc_u32 s101, s21, 0
	global_load_dwordx4 v[182:185], v154, s[100:101] offset:512
	global_load_dwordx4 v[186:189], v154, s[100:101] offset:528
	s_waitcnt vmcnt(20)
	v_pk_fma_f32 v[190:191], v[52:53], v[146:147], v[190:191]
	v_pk_fma_f32 v[192:193], v[54:55], v[148:149], v[192:193]
	v_pk_fma_f32 v[194:195], v[48:49], v[150:151], v[194:195]
	v_pk_fma_f32 v[196:197], v[50:51], v[152:153], v[196:197]
	s_add_u32 s18, s8, 0x10000
	s_addc_u32 s19, s9, 0
	global_store_dwordx4 v154, v[190:193], s[18:19] offset:512
	global_store_dwordx4 v154, v[194:197], s[18:19] offset:528
	s_add_u32 s100, s20, 0xb0000
	s_addc_u32 s101, s21, 0
	global_load_dwordx4 v[190:193], v154, s[100:101] offset:512
	global_load_dwordx4 v[194:197], v154, s[100:101] offset:528
	s_waitcnt vmcnt(20)
	v_pk_fma_f32 v[198:199], v[44:45], v[146:147], v[198:199]
	v_pk_fma_f32 v[200:201], v[46:47], v[148:149], v[200:201]
	v_pk_fma_f32 v[202:203], v[40:41], v[150:151], v[202:203]
	v_pk_fma_f32 v[204:205], v[42:43], v[152:153], v[204:205]
	s_add_u32 s18, s8, 0x20000
	s_addc_u32 s19, s9, 0
	global_store_dwordx4 v154, v[198:201], s[18:19] offset:512
	global_store_dwordx4 v154, v[202:205], s[18:19] offset:528
	s_waitcnt vmcnt(18)
	v_pk_fma_f32 v[228:229], v[36:37], v[146:147], v[228:229]
	v_pk_fma_f32 v[230:231], v[38:39], v[148:149], v[230:231]
	v_pk_fma_f32 v[232:233], v[32:33], v[150:151], v[232:233]
	v_pk_fma_f32 v[234:235], v[34:35], v[152:153], v[234:235]
	s_add_u32 s18, s8, 0x30000
	s_addc_u32 s19, s9, 0
	global_store_dwordx4 v154, v[228:231], s[18:19] offset:512
	global_store_dwordx4 v154, v[232:235], s[18:19] offset:528
	s_waitcnt vmcnt(16)
	v_pk_fma_f32 v[166:167], v[28:29], v[146:147], v[166:167]
	v_pk_fma_f32 v[168:169], v[30:31], v[148:149], v[168:169]
	v_pk_fma_f32 v[170:171], v[24:25], v[150:151], v[170:171]
	v_pk_fma_f32 v[172:173], v[26:27], v[152:153], v[172:173]
	s_add_u32 s18, s8, 0x80000
	s_addc_u32 s19, s9, 0
	global_store_dwordx4 v154, v[166:169], s[18:19] offset:512
	global_store_dwordx4 v154, v[170:173], s[18:19] offset:528
	s_waitcnt vmcnt(14)
	v_pk_fma_f32 v[174:175], v[20:21], v[146:147], v[174:175]
	v_pk_fma_f32 v[176:177], v[22:23], v[148:149], v[176:177]
	v_pk_fma_f32 v[178:179], v[16:17], v[150:151], v[178:179]
	v_pk_fma_f32 v[180:181], v[18:19], v[152:153], v[180:181]
	s_add_u32 s18, s8, 0x90000
	s_addc_u32 s19, s9, 0
	global_store_dwordx4 v154, v[174:177], s[18:19] offset:512
	global_store_dwordx4 v154, v[178:181], s[18:19] offset:528
	s_waitcnt vmcnt(12)
	v_pk_fma_f32 v[182:183], v[12:13], v[146:147], v[182:183]
	v_pk_fma_f32 v[184:185], v[14:15], v[148:149], v[184:185]
	v_pk_fma_f32 v[186:187], v[8:9], v[150:151], v[186:187]
	v_pk_fma_f32 v[188:189], v[10:11], v[152:153], v[188:189]
	s_add_u32 s18, s8, 0xa0000
	s_addc_u32 s19, s9, 0
	global_store_dwordx4 v154, v[182:185], s[18:19] offset:512
	global_store_dwordx4 v154, v[186:189], s[18:19] offset:528
	s_waitcnt vmcnt(10)
	v_pk_fma_f32 v[190:191], v[4:5], v[146:147], v[190:191]
	v_pk_fma_f32 v[192:193], v[6:7], v[148:149], v[192:193]
	v_pk_fma_f32 v[194:195], v[0:1], v[150:151], v[194:195]
	v_pk_fma_f32 v[196:197], v[2:3], v[152:153], v[196:197]
	s_add_u32 s18, s8, 0xb0000
	s_addc_u32 s19, s9, 0
	global_store_dwordx4 v154, v[190:193], s[18:19] offset:512
	global_store_dwordx4 v154, v[194:197], s[18:19] offset:528
	s_mov_b64 s[18:19], -1
	s_cbranch_vccnz .LBB0_97
	s_and_b64 vcc, exec, s[4:5]
	s_cbranch_vccnz .LBB0_96
	s_barrier
	s_branch .LBB0_96

.LBB0_557:
	s_ashr_i32 s11, s39, 3
	s_mul_hi_i32 s13, s11, 0x6000
	s_mulk_i32 s11, 0x6000
	s_add_u32 s18, s31, s11
	s_addc_u32 s19, s34, s13
	v_lshl_add_u32 v154, s39, 8, v156
	v_lshl_add_u32 v155, s38, 8, v158
	v_lshlrev_b32_e32 v154, 12, v154
	v_lshlrev_b32_e32 v155, 2, v155
	v_add_u32_e32 v154, v154, v155
	s_andn2_b64 vcc, exec, s[6:7]
	s_waitcnt lgkmcnt(0)
	global_load_dwordx4 v[128:131], v155, s[18:19]
	global_load_dwordx4 v[132:135], v155, s[18:19] offset:16
	global_load_dwordx4 v[146:149], v155, s[18:19] offset:512
	global_load_dwordx4 v[150:153], v155, s[18:19] offset:528
	s_add_u32 s100, s0, 0x0
	s_addc_u32 s101, s1, 0
	global_load_dwordx4 v[166:169], v154, s[100:101]
	global_load_dwordx4 v[170:173], v154, s[100:101] offset:16
	s_add_u32 s100, s0, 0x10000
	s_addc_u32 s101, s1, 0
	global_load_dwordx4 v[174:177], v154, s[100:101]
	global_load_dwordx4 v[178:181], v154, s[100:101] offset:16
	s_add_u32 s100, s0, 0x20000
	s_addc_u32 s101, s1, 0
	global_load_dwordx4 v[182:185], v154, s[100:101]
	global_load_dwordx4 v[186:189], v154, s[100:101] offset:16
	s_add_u32 s100, s0, 0x30000
	s_addc_u32 s101, s1, 0
	global_load_dwordx4 v[190:193], v154, s[100:101]
	global_load_dwordx4 v[194:197], v154, s[100:101] offset:16
	s_add_u32 s100, s0, 0x80000
	s_addc_u32 s101, s1, 0
	global_load_dwordx4 v[198:201], v154, s[100:101]
	global_load_dwordx4 v[202:205], v154, s[100:101] offset:16
	s_add_u32 s100, s0, 0x90000
	s_addc_u32 s101, s1, 0
	global_load_dwordx4 v[228:231], v154, s[100:101]
	global_load_dwordx4 v[232:235], v154, s[100:101] offset:16
	s_waitcnt vmcnt(10)
	v_pk_fma_f32 v[166:167], v[124:125], v[128:129], v[166:167]
	v_pk_fma_f32 v[168:169], v[126:127], v[130:131], v[168:169]
	v_pk_fma_f32 v[170:171], v[120:121], v[132:133], v[170:171]
	v_pk_fma_f32 v[172:173], v[122:123], v[134:135], v[172:173]
	s_add_u32 s18, s8, 0x0
	s_addc_u32 s19, s9, 0
	global_store_dwordx4 v154, v[166:169], s[18:19]
	global_store_dwordx4 v154, v[170:173], s[18:19] offset:16
	s_add_u32 s100, s0, 0xa0000
	s_addc_u32 s101, s1, 0
	global_load_dwordx4 v[166:169], v154, s[100:101]
	global_load_dwordx4 v[170:173], v154, s[100:101] offset:16
	s_waitcnt vmcnt(12)
	v_pk_fma_f32 v[174:175], v[116:117], v[128:129], v[174:175]
	v_pk_fma_f32 v[176:177], v[118:119], v[130:131], v[176:177]
	v_pk_fma_f32 v[178:179], v[112:113], v[132:133], v[178:179]
	v_pk_fma_f32 v[180:181], v[114:115], v[134:135], v[180:181]
	s_add_u32 s18, s8, 0x10000
	s_addc_u32 s19, s9, 0
	global_store_dwordx4 v154, v[174:177], s[18:19]
	global_store_dwordx4 v154, v[178:181], s[18:19] offset:16
	s_add_u32 s100, s0, 0xb0000
	s_addc_u32 s101, s1, 0
	global_load_dwordx4 v[174:177], v154, s[100:101]
	global_load_dwordx4 v[178:181], v154, s[100:101] offset:16
	s_waitcnt vmcnt(14)
	v_pk_fma_f32 v[182:183], v[108:109], v[128:129], v[182:183]
	v_pk_fma_f32 v[184:185], v[110:111], v[130:131], v[184:185]
	v_pk_fma_f32 v[186:187], v[104:105], v[132:133], v[186:187]
	v_pk_fma_f32 v[188:189], v[106:107], v[134:135], v[188:189]
	s_add_u32 s18, s8, 0x20000
	s_addc_u32 s19, s9, 0
	global_store_dwordx4 v154, v[182:185], s[18:19]
	global_store_dwordx4 v154, v[186:189], s[18:19] offset:16
	s_add_u32 s100, s0, 0x0
	s_addc_u32 s101, s1, 0
	global_load_dwordx4 v[182:185], v154, s[100:101] offset:512
	global_load_dwordx4 v[186:189], v154, s[100:101] offset:528
	s_waitcnt vmcnt(16)
	v_pk_fma_f32 v[190:191], v[100:101], v[128:129], v[190:191]
	v_pk_fma_f32 v[192:193], v[102:103], v[130:131], v[192:193]
	v_pk_fma_f32 v[194:195], v[96:97], v[132:133], v[194:195]
	v_pk_fma_f32 v[196:197], v[98:99], v[134:135], v[196:197]
	s_add_u32 s18, s8, 0x30000
	s_addc_u32 s19, s9, 0
	global_store_dwordx4 v154, v[190:193], s[18:19]
	global_store_dwordx4 v154, v[194:197], s[18:19] offset:16
	s_add_u32 s100, s0, 0x10000
	s_addc_u32 s101, s1, 0
	global_load_dwordx4 v[190:193], v154, s[100:101] offset:512
	global_load_dwordx4 v[194:197], v154, s[100:101] offset:528
	s_waitcnt vmcnt(18)
	v_pk_fma_f32 v[198:199], v[92:93], v[128:129], v[198:199]
	v_pk_fma_f32 v[200:201], v[94:95], v[130:131], v[200:201]
	v_pk_fma_f32 v[202:203], v[88:89], v[132:133], v[202:203]
	v_pk_fma_f32 v[204:205], v[90:91], v[134:135], v[204:205]
	s_add_u32 s18, s8, 0x80000
	s_addc_u32 s19, s9, 0
	global_store_dwordx4 v154, v[198:201], s[18:19]
	global_store_dwordx4 v154, v[202:205], s[18:19] offset:16
	s_add_u32 s100, s0, 0x20000
	s_addc_u32 s101, s1, 0
	global_load_dwordx4 v[198:201], v154, s[100:101] offset:512
	global_load_dwordx4 v[202:205], v154, s[100:101] offset:528
	s_waitcnt vmcnt(20)
	v_pk_fma_f32 v[228:229], v[84:85], v[128:129], v[228:229]
	v_pk_fma_f32 v[230:231], v[86:87], v[130:131], v[230:231]
	v_pk_fma_f32 v[232:233], v[80:81], v[132:133], v[232:233]
	v_pk_fma_f32 v[234:235], v[82:83], v[134:135], v[234:235]
	s_add_u32 s18, s8, 0x90000
	s_addc_u32 s19, s9, 0
	global_store_dwordx4 v154, v[228:231], s[18:19]
	global_store_dwordx4 v154, v[232:235], s[18:19] offset:16
	s_add_u32 s100, s0, 0x30000
	s_addc_u32 s101, s1, 0
	global_load_dwordx4 v[228:231], v154, s[100:101] offset:512
	global_load_dwordx4 v[232:235], v154, s[100:101] offset:528
	s_waitcnt vmcnt(20)
	v_pk_fma_f32 v[166:167], v[76:77], v[128:129], v[166:167]
	v_pk_fma_f32 v[168:169], v[78:79], v[130:131], v[168:169]
	v_pk_fma_f32 v[170:171], v[72:73], v[132:133], v[170:171]
	v_pk_fma_f32 v[172:173], v[74:75], v[134:135], v[172:173]
	s_add_u32 s18, s8, 0xa0000
	s_addc_u32 s19, s9, 0
	global_store_dwordx4 v154, v[166:169], s[18:19]
	global_store_dwordx4 v154, v[170:173], s[18:19] offset:16
	s_add_u32 s100, s0, 0x80000
	s_addc_u32 s101, s1, 0
	global_load_dwordx4 v[166:169], v154, s[100:101] offset:512
	global_load_dwordx4 v[170:173], v154, s[100:101] offset:528
	s_waitcnt vmcnt(20)
	v_pk_fma_f32 v[174:175], v[68:69], v[128:129], v[174:175]
	v_pk_fma_f32 v[176:177], v[70:71], v[130:131], v[176:177]
	v_pk_fma_f32 v[178:179], v[56:57], v[132:133], v[178:179]
	v_pk_fma_f32 v[180:181], v[58:59], v[134:135], v[180:181]
	s_add_u32 s18, s8, 0xb0000
	s_addc_u32 s19, s9, 0
	global_store_dwordx4 v154, v[174:177], s[18:19]
	global_store_dwordx4 v154, v[178:181], s[18:19] offset:16
	s_add_u32 s100, s0, 0x90000
	s_addc_u32 s101, s1, 0
	global_load_dwordx4 v[174:177], v154, s[100:101] offset:512
	global_load_dwordx4 v[178:181], v154, s[100:101] offset:528
	s_waitcnt vmcnt(20)
	v_pk_fma_f32 v[182:183], v[64:65], v[146:147], v[182:183]
	v_pk_fma_f32 v[184:185], v[66:67], v[148:149], v[184:185]
	v_pk_fma_f32 v[186:187], v[60:61], v[150:151], v[186:187]
	v_pk_fma_f32 v[188:189], v[62:63], v[152:153], v[188:189]
	s_add_u32 s18, s8, 0x0
	s_addc_u32 s19, s9, 0
	global_store_dwordx4 v154, v[182:185], s[18:19] offset:512
	global_store_dwordx4 v154, v[186:189], s[18:19] offset:528
	s_add_u32 s100, s0, 0xa0000
	s_addc_u32 s101, s1, 0
	global_load_dwordx4 v[182:185], v154, s[100:101] offset:512
	global_load_dwordx4 v[186:189], v154, s[100:101] offset:528
	s_waitcnt vmcnt(20)
	v_pk_fma_f32 v[190:191], v[52:53], v[146:147], v[190:191]
	v_pk_fma_f32 v[192:193], v[54:55], v[148:149], v[192:193]
	v_pk_fma_f32 v[194:195], v[48:49], v[150:151], v[194:195]
	v_pk_fma_f32 v[196:197], v[50:51], v[152:153], v[196:197]
	s_add_u32 s18, s8, 0x10000
	s_addc_u32 s19, s9, 0
	global_store_dwordx4 v154, v[190:193], s[18:19] offset:512
	global_store_dwordx4 v154, v[194:197], s[18:19] offset:528
	s_add_u32 s100, s0, 0xb0000
	s_addc_u32 s101, s1, 0
	global_load_dwordx4 v[190:193], v154, s[100:101] offset:512
	global_load_dwordx4 v[194:197], v154, s[100:101] offset:528
	s_waitcnt vmcnt(20)
	v_pk_fma_f32 v[198:199], v[44:45], v[146:147], v[198:199]
	v_pk_fma_f32 v[200:201], v[46:47], v[148:149], v[200:201]
	v_pk_fma_f32 v[202:203], v[40:41], v[150:151], v[202:203]
	v_pk_fma_f32 v[204:205], v[42:43], v[152:153], v[204:205]
	s_add_u32 s18, s8, 0x20000
	s_addc_u32 s19, s9, 0
	global_store_dwordx4 v154, v[198:201], s[18:19] offset:512
	global_store_dwordx4 v154, v[202:205], s[18:19] offset:528
	s_waitcnt vmcnt(18)
	v_pk_fma_f32 v[228:229], v[36:37], v[146:147], v[228:229]
	v_pk_fma_f32 v[230:231], v[38:39], v[148:149], v[230:231]
	v_pk_fma_f32 v[232:233], v[32:33], v[150:151], v[232:233]
	v_pk_fma_f32 v[234:235], v[34:35], v[152:153], v[234:235]
	s_add_u32 s18, s8, 0x30000
	s_addc_u32 s19, s9, 0
	global_store_dwordx4 v154, v[228:231], s[18:19] offset:512
	global_store_dwordx4 v154, v[232:235], s[18:19] offset:528
	s_waitcnt vmcnt(16)
	v_pk_fma_f32 v[166:167], v[28:29], v[146:147], v[166:167]
	v_pk_fma_f32 v[168:169], v[30:31], v[148:149], v[168:169]
	v_pk_fma_f32 v[170:171], v[24:25], v[150:151], v[170:171]
	v_pk_fma_f32 v[172:173], v[26:27], v[152:153], v[172:173]
	s_add_u32 s18, s8, 0x80000
	s_addc_u32 s19, s9, 0
	global_store_dwordx4 v154, v[166:169], s[18:19] offset:512
	global_store_dwordx4 v154, v[170:173], s[18:19] offset:528
	s_waitcnt vmcnt(14)
	v_pk_fma_f32 v[174:175], v[20:21], v[146:147], v[174:175]
	v_pk_fma_f32 v[176:177], v[22:23], v[148:149], v[176:177]
	v_pk_fma_f32 v[178:179], v[16:17], v[150:151], v[178:179]
	v_pk_fma_f32 v[180:181], v[18:19], v[152:153], v[180:181]
	s_add_u32 s18, s8, 0x90000
	s_addc_u32 s19, s9, 0
	global_store_dwordx4 v154, v[174:177], s[18:19] offset:512
	global_store_dwordx4 v154, v[178:181], s[18:19] offset:528
	s_waitcnt vmcnt(12)
	v_pk_fma_f32 v[182:183], v[12:13], v[146:147], v[182:183]
	v_pk_fma_f32 v[184:185], v[14:15], v[148:149], v[184:185]
	v_pk_fma_f32 v[186:187], v[8:9], v[150:151], v[186:187]
	v_pk_fma_f32 v[188:189], v[10:11], v[152:153], v[188:189]
	s_add_u32 s18, s8, 0xa0000
	s_addc_u32 s19, s9, 0
	global_store_dwordx4 v154, v[182:185], s[18:19] offset:512
	global_store_dwordx4 v154, v[186:189], s[18:19] offset:528
	s_waitcnt vmcnt(10)
	v_pk_fma_f32 v[190:191], v[4:5], v[146:147], v[190:191]
	v_pk_fma_f32 v[192:193], v[6:7], v[148:149], v[192:193]
	v_pk_fma_f32 v[194:195], v[0:1], v[150:151], v[194:195]
	v_pk_fma_f32 v[196:197], v[2:3], v[152:153], v[196:197]
	s_add_u32 s18, s8, 0xb0000
	s_addc_u32 s19, s9, 0
	global_store_dwordx4 v154, v[190:193], s[18:19] offset:512
	global_store_dwordx4 v154, v[194:197], s[18:19] offset:528
	s_mov_b64 s[18:19], -1
	s_cbranch_vccnz .LBB0_546
	s_and_b64 vcc, exec, s[4:5]
	s_cbranch_vccnz .LBB0_545
	s_barrier
	s_branch .LBB0_545
